# P3->G2 grid barrier split: arrive after the SSM part, chunk mixer runs, wait before the GLU GEMM
# baseline (speedup 1.0000x reference)
.Lssm_done:
	s_waitcnt vmcnt(0) lgkmcnt(0)
	s_barrier
	s_mov_b64 s[4:5], exec
	v_readlane_b32 s6, v254, 2
	v_readlane_b32 s7, v254, 3
	s_nop 1
	s_and_b64 s[6:7], s[4:5], s[6:7]
	s_mov_b64 exec, s[6:7]
	s_cbranch_execz .Lp3_arrive_join
	s_getreg_b32 s10, hwreg(HW_REG_XCC_ID, 0, 4)
	v_mov_b32_e32 v2, 0x23fc0
	ds_read_b64 v[2:3], v2
	s_lshl_b32 s10, s10, 6
	s_add_u32 s12, s62, 0x408800
	s_addc_u32 s13, s63, 0
	v_mov_b32_e32 v4, s10
	v_mov_b32_e32 v5, 1
	global_atomic_add v6, v4, v5, s[12:13] sc0
	s_waitcnt vmcnt(0) lgkmcnt(0)
	v_add_u32_e32 v6, 1, v6
	v_cmp_eq_u32_e32 vcc, v6, v2
	s_cbranch_vccz .Lp3_arrive_join
	buffer_wbl2 sc1
	s_waitcnt vmcnt(0)
	v_mov_b32_e32 v4, 0x400
	global_atomic_add v4, v5, s[12:13]
.Lp3_arrive_join:
	s_mov_b64 exec, s[4:5]
	v_and_b32_e32 v1, 15, v190
	v_lshrrev_b32_e32 v114, 1, v190
	v_lshrrev_b32_e32 v115, 2, v190
	v_and_b32_e32 v115, 12, v115

.LBB0_393:
	s_cmp_gt_i32 s97, 4
	s_cselect_b64 s[0:1], -1, 0
	s_and_b64 s[4:5], s[8:9], s[0:1]
	v_readlane_b32 s72, v254, 22
	s_andn2_b64 vcc, exec, s[4:5]
	v_readlane_b32 s82, v254, 32
	v_readlane_b32 s83, v254, 33
	v_readlane_b32 s86, v254, 36
	v_readlane_b32 s87, v254, 37
	v_readlane_b32 s73, v254, 23
	v_readlane_b32 s74, v254, 24
	v_readlane_b32 s75, v254, 25
	v_readlane_b32 s76, v254, 26
	v_readlane_b32 s77, v254, 27
	v_readlane_b32 s78, v254, 28
	v_readlane_b32 s79, v254, 29
	v_readlane_b32 s80, v254, 30
	v_readlane_b32 s81, v254, 31
	v_readlane_b32 s84, v254, 34
	v_readlane_b32 s85, v254, 35
	s_cbranch_vccnz .LBB0_447
	s_waitcnt vmcnt(0) lgkmcnt(0)
	s_barrier
	s_mov_b64 s[4:5], exec
	v_readlane_b32 s6, v254, 2
	v_readlane_b32 s7, v254, 3
	s_nop 1
	s_and_b64 s[6:7], s[4:5], s[6:7]
	s_mov_b64 exec, s[6:7]
	s_cbranch_execz .Lp3_wait_join
	v_mov_b32_e32 v2, 0x23fc4
	ds_read_b32 v3, v2
	s_add_u32 s12, s62, 0x408800
	s_addc_u32 s13, s63, 0
	v_mov_b32_e32 v2, 0x400
	s_mov_b32 s14, 0
.Lp3_spin:
	global_load_dword v4, v2, s[12:13] sc1
	s_waitcnt vmcnt(0) lgkmcnt(0)
	v_cmp_ge_u32_e32 vcc, v4, v3
	s_cbranch_vccnz .Lp3_spin_done
	s_sleep 1
	s_add_u32 s14, s14, 1
	s_cmp_lt_u32 s14, 0x100000
	s_cbranch_scc1 .Lp3_spin

.Lp3_wait_join:
	s_mov_b64 exec, s[4:5]
	s_barrier
